# attention loops: back-edge rotated so the loop-back barrier is the loop head (branch taken before the barrier)
# speedup vs baseline: 1.0026x; 1.0026x over previous
; #define LAS __attribute__((address_space(3)))
; __device__ __forceinline__ unsigned cvtpk(float lo, float hi) { f32x2_t v = {lo, hi}; bf16x2_t b = __builtin_convertvector(v, bf16x2_t); return __builtin_bit_cast(unsigned, b); }
; __device__ __forceinline__ f32x4 mfma16(bf16x8 a, bf16x8 b, f32x4 c) { return __builtin_amdgcn_mfma_f32_16x16x32_bf16(a, b, c, 0, 0, 0); }
; __device__ __forceinline__ void attn_unit(LAS unsigned char* lds, const bf16_t* Q, const bf16_t* KV, const bf16_t* KR, bf16_t* MIX, size_t qrow0, size_t krow0, int ntiles, int h, const int tid) {
;     ...
;   u32x4 rk = *(const u32x4*)gk, rv = *(const u32x4*)(gk + 64), rr = (u32x4){0, 0, 0, 0};
;   if (tid < 256) rr = *(const u32x4*)gr;
;   __syncthreads();
;   attn_stage(lds, tid, rk, rv, rr);
;   __syncthreads();
;   for (int t = 0; t < ntiles; ++t) {
;     LAS unsigned char* buf = lds + (t & 1) * AT_BUF;
;     const bool more = (t + 1 < ntiles);
;     if (more) { const bf16_t* g2 = gk + (size_t)(t + 1) * 64 * 1024; rk = *(const u32x4*)g2; rv = *(const u32x4*)(g2 + 64); if (tid < 256) rr = *(const u32x4*)(gr + (size_t)(t + 1) * 64 * 32); }
;     const LAS bf16_t* Ks = (const LAS bf16_t*)buf; const LAS bf16_t* Vs = (const LAS bf16_t*)(buf + 64 * AT_KSTR * 2);
;     f32x4 s[4][2];
; #pragma unroll
;     for (int kb = 0; kb < 4; ++kb) {
;       bf16x8 kf[3];
; #pragma unroll
;       for (int ks = 0; ks < 3; ++ks) kf[ks] = *(const LAS bf16x8*)(Ks + (kb * 16 + c16) * AT_KSTR + ks * 32 + quad * 8);
;     ...
;     for (int s2 = 0; s2 < 2; ++s2) {
;       bf16x8 pf[2];
; #pragma unroll
;       for (int qb = 0; qb < 2; ++qb) { u32x4 w; w.x = cvtpk(s[2 * s2][qb][0], s[2 * s2][qb][1]); w.y = cvtpk(s[2 * s2][qb][2], s[2 * s2][qb][3]);
;         w.z = cvtpk(s[2 * s2 + 1][qb][0], s[2 * s2 + 1][qb][1]); w.w = cvtpk(s[2 * s2 + 1][qb][2], s[2 * s2 + 1][qb][3]); pf[qb] = __builtin_bit_cast(bf16x8, w);
;         lacc[qb] = mfma16(ones, pf[qb], lacc[qb]); }
;       const LAS bf16_t* vb = Vs + (32 * s2 + 4 * quad + tq) * AT_VSTR + 4 * tp;
; #pragma unroll
;       for (int eb = 0; eb < 4; ++eb) {
;         const u32x2 lo = tr_rd(vb + 16 * eb), hi = tr_rd(vb + 16 * AT_VSTR + 16 * eb);
;         const u32x4 vv = (u32x4){lo.x, lo.y, hi.x, hi.y}; const bf16x8 vf = __builtin_bit_cast(bf16x8, vv);
; #pragma unroll
;         for (int qb = 0; qb < 2; ++qb) o[qb][eb] = mfma16(vf, pf[qb], o[qb][eb]);
.LBB0_382:
	s_or_b64 exec, exec, s[4:5]
	s_and_b32 s4, s8, 7
	s_mul_i32 s5, s4, 0x84000
	s_mul_i32 s4, s4, 0x1080000
	s_lshl_b64 s[0:1], s[0:1], 1
	s_add_u32 s0, s4, s0
	v_or_b32_e32 v0, s5, v121
	s_addc_u32 s1, 0, s1
	v_pk_add_f32 v[2:3], v[2:3], 0 op_sel_hi:[1,0]
	v_lshl_add_u64 v[140:141], v[132:133], 0, v[0:1]
	v_lshl_add_u64 v[142:143], v[134:135], 0, s[0:1]
	s_mov_b32 s4, 2
	s_waitcnt vmcnt(0)
	ds_write_b128 v151, v[72:75] offset:35840
	s_waitcnt lgkmcnt(0)
	s_barrier
	v_mov_b32_e32 v198, 0x3f803f80
	v_mov_b32_e32 v199, v198
	v_mov_b32_e32 v200, v198
	v_mov_b32_e32 v201, v198
	v_xor_b32_e32 v202, 0x80000000, v2
	v_xor_b32_e32 v206, 0x80000000, v3
	v_lshlrev_b32_e32 v176, 1, v154
	v_mov_b32_e32 v203, v202
	v_mov_b32_e32 v204, v202
	v_mov_b32_e32 v205, v202
	v_mov_b32_e32 v207, v206
	v_mov_b32_e32 v208, v206
	v_mov_b32_e32 v209, v206
	s_cmp_lg_u32 s42, 0
	s_cbranch_scc1 .LBB0_384
	global_load_dwordx4 v[76:79], v[142:143], off
	global_load_dwordx4 v[72:75], v[142:143], off offset:128
	s_add_i32 s0, s4, -1
	s_mul_i32 s1, s0, 0xaaab
	s_lshr_b32 s1, s1, 17
	s_mul_i32 s1, s1, 3
	s_sub_i32 s0, s0, s1
	s_mul_i32 s1, s0, 0x5800
	s_add_i32 s5, s1, 0x5800
	s_cmp_eq_u32 s5, 0x10800
	s_cselect_b32 s5, 0, s5
	v_add3_u32 v0, s1, v124, v146
	ds_read_b128 v[170:173], v0
	ds_read_b128 v[210:213], v0 offset:64
	ds_read_b128 v[214:217], v0 offset:128
	ds_read_b128 v[218:221], v0 offset:3328
	ds_read_b128 v[166:169], v0 offset:3392
	s_branch .Lat_B_mid
.Lat_B_head:
	s_barrier
.Lat_B_top:
	global_load_dwordx4 v[76:79], v[142:143], off
	global_load_dwordx4 v[72:75], v[142:143], off offset:128
	s_add_i32 s0, s4, -1
	s_mul_i32 s1, s0, 0xaaab
	s_lshr_b32 s1, s1, 17
	s_mul_i32 s1, s1, 3
	s_sub_i32 s0, s0, s1
	s_mul_i32 s1, s0, 0x5800
	s_add_i32 s5, s1, 0x5800
	s_cmp_eq_u32 s5, 0x10800
	s_cselect_b32 s5, 0, s5
	s_add_i32 s0, s1, 0xffffa800
	s_cmp_lt_i32 s0, 0
	s_cselect_b32 s0, 0xb000, s0
	v_add3_u32 v139, s0, v176, v155
	ds_read_b64_tr_b16 v[170:171], v139 offset:13312
	ds_read_b64_tr_b16 v[172:173], v139 offset:15616
	ds_read_b64_tr_b16 v[210:211], v139 offset:13344
	ds_read_b64_tr_b16 v[212:213], v139 offset:15648
	ds_read_b64_tr_b16 v[214:215], v139 offset:13376
	ds_read_b64_tr_b16 v[216:217], v139 offset:15680
	ds_read_b64_tr_b16 v[218:219], v139 offset:13408
	ds_read_b64_tr_b16 v[220:221], v139 offset:15712
	ds_read_b64_tr_b16 v[240:241], v139 offset:17920
	ds_read_b64_tr_b16 v[242:243], v139 offset:20224
	ds_read_b64_tr_b16 v[244:245], v139 offset:17952
	ds_read_b64_tr_b16 v[246:247], v139 offset:20256
	ds_read_b64_tr_b16 v[158:159], v139 offset:17984
	ds_read_b64_tr_b16 v[160:161], v139 offset:20288
	s_waitcnt lgkmcnt(12)
	v_mfma_f32_16x16x32_bf16 v[52:55], v[170:173], v[80:83], v[52:55]
	v_mfma_f32_16x16x32_bf16 v[48:51], v[170:173], v[88:91], v[48:51]
	ds_read_b64_tr_b16 v[162:163], v139 offset:18016
	ds_read_b64_tr_b16 v[164:165], v139 offset:20320
	v_mfma_f32_16x16x32_bf16 v[60:63], v[198:201], v[80:83], v[60:63]
	v_mfma_f32_16x16x32_bf16 v[56:59], v[198:201], v[88:91], v[56:59]
	s_waitcnt lgkmcnt(12)
	v_mfma_f32_16x16x32_bf16 v[68:71], v[210:213], v[80:83], v[68:71]
	v_mfma_f32_16x16x32_bf16 v[64:67], v[210:213], v[88:91], v[64:67]
	s_waitcnt lgkmcnt(10)
	v_mfma_f32_16x16x32_bf16 v[44:47], v[214:217], v[80:83], v[44:47]
	v_mfma_f32_16x16x32_bf16 v[40:43], v[214:217], v[88:91], v[40:43]
	s_waitcnt lgkmcnt(8)
	v_mfma_f32_16x16x32_bf16 v[36:39], v[218:221], v[80:83], v[36:39]
	v_mfma_f32_16x16x32_bf16 v[32:35], v[218:221], v[88:91], v[32:35]
	v_add3_u32 v0, s1, v124, v146
	ds_read_b128 v[170:173], v0
	ds_read_b128 v[210:213], v0 offset:64
	ds_read_b128 v[214:217], v0 offset:128
	ds_read_b128 v[218:221], v0 offset:3328
	ds_read_b128 v[166:169], v0 offset:3392
	v_mfma_f32_16x16x32_bf16 v[60:63], v[198:201], v[96:99], v[60:63]
	v_mfma_f32_16x16x32_bf16 v[56:59], v[198:201], v[104:107], v[56:59]
	s_waitcnt lgkmcnt(11)
	v_mfma_f32_16x16x32_bf16 v[52:55], v[240:243], v[96:99], v[52:55]
	v_mfma_f32_16x16x32_bf16 v[48:51], v[240:243], v[104:107], v[48:51]
	s_waitcnt lgkmcnt(9)
	v_mfma_f32_16x16x32_bf16 v[68:71], v[244:247], v[96:99], v[68:71]
	v_mfma_f32_16x16x32_bf16 v[64:67], v[244:247], v[104:107], v[64:67]
	s_waitcnt lgkmcnt(7)
	v_mfma_f32_16x16x32_bf16 v[44:47], v[158:161], v[96:99], v[44:47]
	v_mfma_f32_16x16x32_bf16 v[40:43], v[158:161], v[104:107], v[40:43]
	s_waitcnt lgkmcnt(5)
	v_mfma_f32_16x16x32_bf16 v[36:39], v[162:165], v[96:99], v[36:39]
	v_mfma_f32_16x16x32_bf16 v[32:35], v[162:165], v[104:107], v[32:35]

; #define LAS __attribute__((address_space(3)))
; __device__ __forceinline__ unsigned cvtpk(float lo, float hi) { f32x2_t v = {lo, hi}; bf16x2_t b = __builtin_convertvector(v, bf16x2_t); return __builtin_bit_cast(unsigned, b); }
; __device__ __forceinline__ f32x4 mfma16(bf16x8 a, bf16x8 b, f32x4 c) { return __builtin_amdgcn_mfma_f32_16x16x32_bf16(a, b, c, 0, 0, 0); }
; __device__ __forceinline__ u32x2 tr_rd(const LAS bf16_t* p) { return __builtin_bit_cast(u32x2, __builtin_amdgcn_ds_read_tr16_b64_v4i16((LAS v4i16_t*)p)); }
; __device__ __forceinline__ void attn_unit(LAS unsigned char* lds, const bf16_t* Q, const bf16_t* KV, const bf16_t* KR, bf16_t* MIX, size_t qrow0, size_t krow0, int ntiles, int h, const int tid) {
;     ...
;         for (int r = 0; r < 4; ++r) s[kb][qb][r] = __builtin_amdgcn_exp2f(s[kb][qb][r]);
;     }
; #pragma unroll
;     for (int s2 = 0; s2 < 2; ++s2) {
;       bf16x8 pf[2];
; #pragma unroll
;       for (int qb = 0; qb < 2; ++qb) { u32x4 w; w.x = cvtpk(s[2 * s2][qb][0], s[2 * s2][qb][1]); w.y = cvtpk(s[2 * s2][qb][2], s[2 * s2][qb][3]);
;         w.z = cvtpk(s[2 * s2 + 1][qb][0], s[2 * s2 + 1][qb][1]); w.w = cvtpk(s[2 * s2 + 1][qb][2], s[2 * s2 + 1][qb][3]); pf[qb] = __builtin_bit_cast(bf16x8, w);
;         lacc[qb] = mfma16(ones, pf[qb], lacc[qb]); }
;       const LAS bf16_t* vb = Vs + (32 * s2 + 4 * quad + tq) * AT_VSTR + 4 * tp;
; #pragma unroll
;       for (int eb = 0; eb < 4; ++eb) {
;         const u32x2 lo = tr_rd(vb + 16 * eb), hi = tr_rd(vb + 16 * AT_VSTR + 16 * eb);
;         const u32x4 vv = (u32x4){lo.x, lo.y, hi.x, hi.y}; const bf16x8 vf = __builtin_bit_cast(bf16x8, vv);
; #pragma unroll
;         for (int qb = 0; qb < 2; ++qb) o[qb][eb] = mfma16(vf, pf[qb], o[qb][eb]);
;       }
;     }
;     if (more) attn_stage(lds + ((t + 1) & 1) * AT_BUF, tid, rk, rv, rr);
;     __syncthreads();
.Lat_backB:
	v_exp_f32_e32 v80, v80
	v_exp_f32_e32 v81, v81
	v_exp_f32_e32 v82, v82
	v_exp_f32_e32 v83, v83
	v_exp_f32_e32 v84, v84
	v_exp_f32_e32 v85, v85
	v_exp_f32_e32 v86, v86
	v_exp_f32_e32 v87, v87
	v_cvt_pk_bf16_f32 v80, v80, v81
	v_cvt_pk_bf16_f32 v81, v82, v83
	v_cvt_pk_bf16_f32 v82, v84, v85
	v_cvt_pk_bf16_f32 v83, v86, v87
	v_exp_f32_e32 v88, v88
	v_exp_f32_e32 v89, v89
	v_exp_f32_e32 v90, v90
	v_exp_f32_e32 v91, v91
	v_exp_f32_e32 v92, v92
	v_exp_f32_e32 v93, v93
	v_exp_f32_e32 v94, v94
	v_exp_f32_e32 v95, v95
	v_cvt_pk_bf16_f32 v88, v88, v89
	v_cvt_pk_bf16_f32 v89, v90, v91
	v_cvt_pk_bf16_f32 v90, v92, v93
	v_cvt_pk_bf16_f32 v91, v94, v95
	v_exp_f32_e32 v96, v96
	v_exp_f32_e32 v97, v97
	v_exp_f32_e32 v98, v98
	v_exp_f32_e32 v99, v99
	v_exp_f32_e32 v100, v100
	v_exp_f32_e32 v101, v101
	v_exp_f32_e32 v102, v102
	v_exp_f32_e32 v103, v103
	v_cvt_pk_bf16_f32 v96, v96, v97
	v_cvt_pk_bf16_f32 v97, v98, v99
	v_cvt_pk_bf16_f32 v98, v100, v101
	v_cvt_pk_bf16_f32 v99, v102, v103
	v_exp_f32_e32 v104, v104
	v_exp_f32_e32 v105, v105
	v_exp_f32_e32 v106, v106
	v_exp_f32_e32 v107, v107
	v_exp_f32_e32 v108, v108
	v_exp_f32_e32 v109, v109
	v_exp_f32_e32 v110, v110
	v_exp_f32_e32 v111, v111
	v_cvt_pk_bf16_f32 v104, v104, v105
	v_cvt_pk_bf16_f32 v105, v106, v107
	v_cvt_pk_bf16_f32 v106, v108, v109
	v_cvt_pk_bf16_f32 v107, v110, v111
	s_waitcnt vmcnt(0)
	ds_write_b128 v0, v[76:79]
	ds_write_b128 v177, v[72:75] offset:13312
	s_mov_b64 s[0:1], 0x1000
	s_add_i32 s4, s4, 1
	v_lshl_add_u64 v[140:141], v[140:141], 0, s[0:1]
	s_mov_b64 s[0:1], 0x20000
	v_lshl_add_u64 v[142:143], v[142:143], 0, s[0:1]
	s_cmpk_lg_i32 s4, 0x84
	s_waitcnt lgkmcnt(0)
	s_cbranch_scc1 .Lat_B_head
	s_barrier
	s_movk_i32 s0, 0x5800
	v_add3_u32 v139, s0, v176, v155
	ds_read_b64_tr_b16 v[170:171], v139 offset:13312
	ds_read_b64_tr_b16 v[172:173], v139 offset:15616
	ds_read_b64_tr_b16 v[210:211], v139 offset:13344
	ds_read_b64_tr_b16 v[212:213], v139 offset:15648
	ds_read_b64_tr_b16 v[214:215], v139 offset:13376
	ds_read_b64_tr_b16 v[216:217], v139 offset:15680
	ds_read_b64_tr_b16 v[218:219], v139 offset:13408
	ds_read_b64_tr_b16 v[220:221], v139 offset:15712
	ds_read_b64_tr_b16 v[240:241], v139 offset:17920
	ds_read_b64_tr_b16 v[242:243], v139 offset:20224
	ds_read_b64_tr_b16 v[244:245], v139 offset:17952
	ds_read_b64_tr_b16 v[246:247], v139 offset:20256
	ds_read_b64_tr_b16 v[158:159], v139 offset:17984
	ds_read_b64_tr_b16 v[160:161], v139 offset:20288
	s_waitcnt lgkmcnt(12)
	v_mfma_f32_16x16x32_bf16 v[52:55], v[170:173], v[80:83], v[52:55]
	v_mfma_f32_16x16x32_bf16 v[48:51], v[170:173], v[88:91], v[48:51]
	ds_read_b64_tr_b16 v[162:163], v139 offset:18016
	ds_read_b64_tr_b16 v[164:165], v139 offset:20320
	v_mfma_f32_16x16x32_bf16 v[60:63], v[198:201], v[80:83], v[60:63]
	v_mfma_f32_16x16x32_bf16 v[56:59], v[198:201], v[88:91], v[56:59]
	s_waitcnt lgkmcnt(12)
	v_mfma_f32_16x16x32_bf16 v[68:71], v[210:213], v[80:83], v[68:71]
	v_mfma_f32_16x16x32_bf16 v[64:67], v[210:213], v[88:91], v[64:67]
	s_waitcnt lgkmcnt(10)
	v_mfma_f32_16x16x32_bf16 v[44:47], v[214:217], v[80:83], v[44:47]
	v_mfma_f32_16x16x32_bf16 v[40:43], v[214:217], v[88:91], v[40:43]
	s_waitcnt lgkmcnt(8)
	v_mfma_f32_16x16x32_bf16 v[36:39], v[218:221], v[80:83], v[36:39]
	v_mfma_f32_16x16x32_bf16 v[32:35], v[218:221], v[88:91], v[32:35]
	v_mfma_f32_16x16x32_bf16 v[60:63], v[198:201], v[96:99], v[60:63]
	v_mfma_f32_16x16x32_bf16 v[56:59], v[198:201], v[104:107], v[56:59]
	s_waitcnt lgkmcnt(6)
	v_mfma_f32_16x16x32_bf16 v[52:55], v[240:243], v[96:99], v[52:55]
	v_mfma_f32_16x16x32_bf16 v[48:51], v[240:243], v[104:107], v[48:51]
	s_waitcnt lgkmcnt(4)
	v_mfma_f32_16x16x32_bf16 v[68:71], v[244:247], v[96:99], v[68:71]
	v_mfma_f32_16x16x32_bf16 v[64:67], v[244:247], v[104:107], v[64:67]
	s_waitcnt lgkmcnt(2)
	v_mfma_f32_16x16x32_bf16 v[44:47], v[158:161], v[96:99], v[44:47]
	v_mfma_f32_16x16x32_bf16 v[40:43], v[158:161], v[104:107], v[40:43]
	s_waitcnt lgkmcnt(0)
	v_mfma_f32_16x16x32_bf16 v[36:39], v[162:165], v[96:99], v[36:39]
	v_mfma_f32_16x16x32_bf16 v[32:35], v[162:165], v[104:107], v[32:35]
	s_branch .LBB0_392

; __device__ __forceinline__ void attn_unit(LAS unsigned char* lds, const bf16_t* Q, const bf16_t* KV, const bf16_t* KR, bf16_t* MIX, size_t qrow0, size_t krow0, int ntiles, int h, const int tid) {
;     ...
;     if (more) { const bf16_t* g2 = gk + (size_t)(t + 1) * 64 * 1024; rk = *(const u32x4*)g2; rv = *(const u32x4*)(g2 + 64); if (tid < 256) rr = *(const u32x4*)(gr + (size_t)(t + 1) * 64 * 32); }
.Lat_rA2:
	s_branch .Lat_backA
.Lat_A_head:
	s_barrier
.LBB0_384:
	global_load_dwordx4 v[76:79], v[142:143], off
	global_load_dwordx4 v[72:75], v[142:143], off offset:128
	s_and_saveexec_b64 s[0:1], s[42:43]
	s_cbranch_execz .LBB0_386
	global_load_dwordx4 v[28:31], v[140:141], off

; __device__ __forceinline__ void attn_unit(LAS unsigned char* lds, const bf16_t* Q, const bf16_t* KV, const bf16_t* KR, bf16_t* MIX, size_t qrow0, size_t krow0, int ntiles, int h, const int tid) {
;     ...
;     if (more) attn_stage(lds + ((t + 1) & 1) * AT_BUF, tid, rk, rv, rr);
;     __syncthreads();
.LBB0_383:
	s_or_b64 exec, exec, s[0:1]
	s_mov_b64 s[0:1], 0x1000
	s_add_i32 s4, s4, 1
	v_lshl_add_u64 v[140:141], v[140:141], 0, s[0:1]
	s_mov_b64 s[0:1], 0x20000
	v_lshl_add_u64 v[142:143], v[142:143], 0, s[0:1]
	s_cmpk_lg_i32 s4, 0x84
	s_waitcnt lgkmcnt(0)
	s_cbranch_scc1 .Lat_A_head
	s_barrier
